# PLE residual epilogue: paired 8-byte agent-scope gate loads merged into 16-byte loads; barrier arrival-counter polling and attention staging edits kept
# speedup vs baseline: 1.0062x; 1.0040x over previous
.LBB0_925:
	v_lshl_add_u32 v138, s60, 8, v140
	v_lshl_or_b32 v136, s26, 8, v142
	v_ashrrev_i32_e32 v139, 31, v138
	v_ashrrev_i32_e32 v137, 31, v136
	v_lshlrev_b64 v[144:145], 10, v[138:139]
	v_lshl_add_u64 v[152:153], v[144:145], 0, v[136:137]
	v_lshlrev_b64 v[154:155], 2, v[152:153]
	v_lshlrev_b64 v[152:153], 1, v[152:153]
	v_lshl_add_u64 v[156:157], s[28:29], 0, v[154:155]
	v_lshl_add_u64 v[158:159], s[46:47], 0, v[152:153]
	global_load_dwordx4 v[144:147], v[156:157], off offset:16
	global_load_dwordx4 v[148:151], v[156:157], off
	global_load_dwordx4 v[160:163], v[158:159], off sc1
	v_lshl_add_u64 v[154:155], s[34:35], 0, v[154:155]
	v_lshl_add_u64 v[152:153], s[36:37], 0, v[152:153]
	s_lshl_b32 s60, s26, 2
	s_ashr_i32 s61, s60, 31
	s_waitcnt vmcnt(0)
	v_lshlrev_b32_e32 v164, 16, v160
	v_and_b32_e32 v160, 0xffff0000, v160
	v_lshlrev_b32_e32 v165, 16, v161
	v_and_b32_e32 v161, 0xffff0000, v161
	v_lshlrev_b32_e32 v166, 16, v162
	v_and_b32_e32 v162, 0xffff0000, v162
	v_lshlrev_b32_e32 v167, 16, v163
	v_and_b32_e32 v163, 0xffff0000, v163
	v_mul_f32_e32 v126, v126, v164
	v_mul_f32_e32 v127, v127, v160
	v_mul_f32_e32 v128, v128, v165
	v_mul_f32_e32 v129, v129, v161
	v_mul_f32_e32 v160, v122, v166
	v_mul_f32_e32 v161, v123, v162
	v_mul_f32_e32 v162, v124, v167
	v_mul_f32_e32 v163, v125, v163
	v_pk_add_f32 v[124:125], v[150:151], v[128:129]
	v_pk_add_f32 v[122:123], v[148:149], v[126:127]
	v_pk_add_f32 v[128:129], v[146:147], v[162:163]
	v_pk_add_f32 v[126:127], v[144:145], v[160:161]
	v_cvt_pk_bf16_f32 v144, v122, v123
	v_cvt_pk_bf16_f32 v145, v124, v125
	v_cvt_pk_bf16_f32 v146, v126, v127
	v_cvt_pk_bf16_f32 v147, v128, v129
	global_store_dwordx4 v[154:155], v[122:125], off
	global_store_dwordx4 v[154:155], v[126:129], off offset:16
	global_store_dwordx4 v[152:153], v[144:147], off
	global_load_dwordx4 v[144:147], v[156:157], off offset:528
	s_nop 0
	global_load_dwordx4 v[148:151], v[156:157], off offset:512
	s_nop 0
	global_load_dwordx4 v[156:159], v[158:159], off offset:256 sc1
	v_mul_f32_e32 v123, v123, v123
	v_mul_f32_e32 v125, v125, v125
	v_mul_f32_e32 v127, v127, v127
	v_mul_f32_e32 v129, v129, v129
	v_fmac_f32_e32 v123, v122, v122
	v_fmac_f32_e32 v125, v124, v124
	v_fmac_f32_e32 v127, v126, v126
	v_fmac_f32_e32 v129, v128, v128
	v_add_f32_e32 v122, v123, v125
	v_add_f32_e32 v123, v127, v129
	v_add_f32_e32 v126, v122, v123
	s_waitcnt vmcnt(0)
	v_lshlrev_b32_e32 v122, 16, v156
	v_and_b32_e32 v123, 0xffff0000, v156
	v_lshlrev_b32_e32 v124, 16, v157
	v_and_b32_e32 v125, 0xffff0000, v157
	s_waitcnt vmcnt(0)
	v_lshlrev_b32_e32 v127, 16, v158
	v_and_b32_e32 v128, 0xffff0000, v158
	v_lshlrev_b32_e32 v129, 16, v159
	v_and_b32_e32 v156, 0xffff0000, v159
	v_mul_f32_e32 v118, v118, v122
	v_mul_f32_e32 v119, v119, v123
	v_mul_f32_e32 v120, v120, v124
	v_mul_f32_e32 v121, v121, v125
	v_mul_f32_e32 v122, v114, v127
	v_mul_f32_e32 v123, v115, v128
	v_mul_f32_e32 v124, v116, v129
	v_mul_f32_e32 v125, v117, v156
	v_pk_add_f32 v[116:117], v[150:151], v[120:121]
	v_pk_add_f32 v[114:115], v[148:149], v[118:119]
	v_pk_add_f32 v[120:121], v[146:147], v[124:125]
	v_pk_add_f32 v[118:119], v[144:145], v[122:123]
	global_store_dwordx4 v[154:155], v[114:117], off offset:512
	global_store_dwordx4 v[154:155], v[118:121], off offset:528
	v_cvt_pk_bf16_f32 v122, v114, v115
	v_cvt_pk_bf16_f32 v123, v116, v117
	v_cvt_pk_bf16_f32 v124, v118, v119
	v_cvt_pk_bf16_f32 v125, v120, v121
	v_mul_f32_e32 v115, v115, v115
	v_mul_f32_e32 v117, v117, v117
	v_mul_f32_e32 v119, v119, v119
	v_mul_f32_e32 v121, v121, v121
	v_fmac_f32_e32 v115, v114, v114
	v_fmac_f32_e32 v117, v116, v116
	v_fmac_f32_e32 v119, v118, v118
	v_fmac_f32_e32 v121, v120, v120
	global_store_dwordx4 v[152:153], v[122:125], off offset:256
	v_mbcnt_lo_u32_b32 v114, -1, 0
	v_mbcnt_hi_u32_b32 v114, -1, v114
	v_add_f32_e32 v115, v115, v117
	v_add_f32_e32 v116, v119, v121
	v_lshlrev_b32_e32 v114, 2, v114
	v_add_f32_e32 v115, v115, v116
	v_xor_b32_e32 v114, 64, v114
	v_add_f32_e32 v115, v126, v115
	ds_bpermute_b32 v114, v114, v115
	s_waitcnt lgkmcnt(0)
	v_add_f32_e32 v114, v115, v114
	v_mov_b32_e32 v115, v114
	s_nop 1
	v_permlane32_swap_b32_e32 v114, v115
	s_and_saveexec_b64 s[26:27], s[42:43]
	s_cbranch_execz .LBB0_927
	v_lshlrev_b64 v[116:117], 6, v[138:139]
	v_lshl_add_u64 v[116:117], s[38:39], 0, v[116:117]
	v_lshl_add_u64 v[116:117], s[60:61], 2, v[116:117]
	s_lshl_b32 s90, s73, 2
	v_lshl_add_u64 v[116:117], v[116:117], 0, s[90:91]
	v_add_f32_e32 v114, v114, v115
	global_store_dword v[116:117], v114, off
.LBB0_927:
	s_or_b64 exec, exec, s[26:27]
	v_or_b32_e32 v114, 16, v138
	v_ashrrev_i32_e32 v115, 31, v114
	v_lshlrev_b64 v[116:117], 10, v[114:115]
	v_lshl_add_u64 v[124:125], v[116:117], 0, v[136:137]
	v_lshlrev_b64 v[126:127], 2, v[124:125]
	v_lshlrev_b64 v[124:125], 1, v[124:125]
	v_lshl_add_u64 v[128:129], s[28:29], 0, v[126:127]
	v_lshl_add_u64 v[144:145], s[46:47], 0, v[124:125]
	global_load_dwordx4 v[116:119], v[128:129], off offset:16
	global_load_dwordx4 v[120:123], v[128:129], off
	global_load_dwordx4 v[146:149], v[144:145], off sc1
	v_lshl_add_u64 v[126:127], s[34:35], 0, v[126:127]
	v_lshl_add_u64 v[124:125], s[36:37], 0, v[124:125]
	s_waitcnt vmcnt(0)
	v_lshlrev_b32_e32 v139, 16, v146
	v_and_b32_e32 v146, 0xffff0000, v146
	v_lshlrev_b32_e32 v150, 16, v147
	v_and_b32_e32 v147, 0xffff0000, v147
	s_waitcnt vmcnt(0)
	v_lshlrev_b32_e32 v151, 16, v148
	v_and_b32_e32 v148, 0xffff0000, v148
	v_lshlrev_b32_e32 v152, 16, v149
	v_and_b32_e32 v149, 0xffff0000, v149
	v_mul_f32_e32 v110, v110, v139
	v_mul_f32_e32 v111, v111, v146
	v_mul_f32_e32 v112, v112, v150
	v_mul_f32_e32 v113, v113, v147
	v_mul_f32_e32 v146, v106, v151
	v_mul_f32_e32 v147, v107, v148
	v_mul_f32_e32 v148, v108, v152
	v_mul_f32_e32 v149, v109, v149
	v_pk_add_f32 v[108:109], v[122:123], v[112:113]
	v_pk_add_f32 v[106:107], v[120:121], v[110:111]
	v_pk_add_f32 v[112:113], v[118:119], v[148:149]
	v_pk_add_f32 v[110:111], v[116:117], v[146:147]
	v_cvt_pk_bf16_f32 v116, v106, v107
	v_cvt_pk_bf16_f32 v117, v108, v109
	v_cvt_pk_bf16_f32 v118, v110, v111
	v_cvt_pk_bf16_f32 v119, v112, v113
	global_store_dwordx4 v[126:127], v[106:109], off
	global_store_dwordx4 v[126:127], v[110:113], off offset:16
	global_store_dwordx4 v[124:125], v[116:119], off
	global_load_dwordx4 v[116:119], v[128:129], off offset:528
	s_nop 0
	global_load_dwordx4 v[120:123], v[128:129], off offset:512
	s_nop 0
	global_load_dwordx2 v[128:129], v[144:145], off offset:256 sc1
	s_nop 0
	global_load_dwordx2 v[144:145], v[144:145], off offset:264 sc1
	v_mul_f32_e32 v107, v107, v107
	v_mul_f32_e32 v109, v109, v109
	v_mul_f32_e32 v111, v111, v111
	v_mul_f32_e32 v113, v113, v113
	v_fmac_f32_e32 v107, v106, v106
	v_fmac_f32_e32 v109, v108, v108
	v_fmac_f32_e32 v111, v110, v110
	v_fmac_f32_e32 v113, v112, v112
	v_add_f32_e32 v106, v107, v109
	v_add_f32_e32 v107, v111, v113
	v_add_f32_e32 v110, v106, v107
	s_waitcnt vmcnt(1)
	v_lshlrev_b32_e32 v106, 16, v128
	v_and_b32_e32 v107, 0xffff0000, v128
	v_lshlrev_b32_e32 v108, 16, v129
	v_and_b32_e32 v109, 0xffff0000, v129
	s_waitcnt vmcnt(0)
	v_lshlrev_b32_e32 v111, 16, v144
	v_and_b32_e32 v112, 0xffff0000, v144
	v_lshlrev_b32_e32 v113, 16, v145
	v_and_b32_e32 v128, 0xffff0000, v145
	v_mul_f32_e32 v102, v102, v106
	v_mul_f32_e32 v103, v103, v107
	v_mul_f32_e32 v104, v104, v108
	v_mul_f32_e32 v105, v105, v109
	v_mul_f32_e32 v106, v98, v111
	v_mul_f32_e32 v107, v99, v112
	v_mul_f32_e32 v108, v100, v113
	v_mul_f32_e32 v109, v101, v128
	v_pk_add_f32 v[100:101], v[122:123], v[104:105]
	v_pk_add_f32 v[98:99], v[120:121], v[102:103]
	v_pk_add_f32 v[104:105], v[118:119], v[108:109]
	v_pk_add_f32 v[102:103], v[116:117], v[106:107]
	global_store_dwordx4 v[126:127], v[98:101], off offset:512
	global_store_dwordx4 v[126:127], v[102:105], off offset:528
	v_cvt_pk_bf16_f32 v106, v98, v99
	v_cvt_pk_bf16_f32 v107, v100, v101
	v_cvt_pk_bf16_f32 v108, v102, v103
	v_cvt_pk_bf16_f32 v109, v104, v105
	v_mul_f32_e32 v99, v99, v99
	v_mul_f32_e32 v101, v101, v101
	v_mul_f32_e32 v103, v103, v103
	v_mul_f32_e32 v105, v105, v105
	v_fmac_f32_e32 v99, v98, v98
	v_fmac_f32_e32 v101, v100, v100
	v_fmac_f32_e32 v103, v102, v102
	v_fmac_f32_e32 v105, v104, v104
	global_store_dwordx4 v[124:125], v[106:109], off offset:256
	v_mbcnt_lo_u32_b32 v98, -1, 0
	v_mbcnt_hi_u32_b32 v98, -1, v98
	v_add_f32_e32 v99, v99, v101
	v_add_f32_e32 v100, v103, v105
	v_lshlrev_b32_e32 v98, 2, v98
	v_add_f32_e32 v99, v99, v100
	v_xor_b32_e32 v98, 64, v98
	v_add_f32_e32 v99, v110, v99
	ds_bpermute_b32 v98, v98, v99
	s_waitcnt lgkmcnt(0)
	v_add_f32_e32 v98, v99, v98
	v_mov_b32_e32 v99, v98
	s_nop 1
	v_permlane32_swap_b32_e32 v98, v99
	s_mov_b64 s[26:27], exec
	v_readlane_b32 s80, v254, 53
	s_and_b64 s[30:31], s[26:27], s[42:43]
	v_readlane_b32 s81, v254, 54
	v_readlane_b32 s84, v254, 57
	v_readlane_b32 s64, v254, 60
	v_readlane_b32 s65, v254, 61
	v_readlane_b32 s77, v254, 62
	v_readlane_b32 s78, v254, 63
	v_readlane_b32 s76, v255, 1
	v_readlane_b32 s66, v255, 4
	v_readlane_b32 s67, v255, 6
	v_mov_b64_e32 v[212:213], 0x100
	v_mov_b64_e32 v[216:217], 0xff
	s_mov_b64 exec, s[30:31]
	s_cbranch_execz .LBB0_929
	v_lshlrev_b64 v[100:101], 6, v[114:115]
	v_lshl_add_u64 v[100:101], s[38:39], 0, v[100:101]
	v_lshl_add_u64 v[100:101], s[60:61], 2, v[100:101]
	s_lshl_b32 s90, s73, 2
	v_lshl_add_u64 v[100:101], v[100:101], 0, s[90:91]
	v_add_f32_e32 v98, v98, v99
	global_store_dword v[100:101], v98, off
.LBB0_929:
	s_or_b64 exec, exec, s[26:27]
	v_or_b32_e32 v98, 32, v138
	v_ashrrev_i32_e32 v99, 31, v98
	v_lshlrev_b64 v[100:101], 10, v[98:99]
	v_lshl_add_u64 v[108:109], v[100:101], 0, v[136:137]
	v_lshlrev_b64 v[110:111], 2, v[108:109]
	v_lshlrev_b64 v[108:109], 1, v[108:109]
	v_lshl_add_u64 v[112:113], s[28:29], 0, v[110:111]
	v_lshl_add_u64 v[114:115], s[46:47], 0, v[108:109]
	global_load_dwordx4 v[100:103], v[112:113], off offset:16
	global_load_dwordx4 v[104:107], v[112:113], off
	global_load_dwordx4 v[116:119], v[114:115], off sc1
	v_lshl_add_u64 v[110:111], s[34:35], 0, v[110:111]
	v_lshl_add_u64 v[108:109], s[36:37], 0, v[108:109]
	s_waitcnt vmcnt(0)
	v_lshlrev_b32_e32 v120, 16, v116
	v_and_b32_e32 v116, 0xffff0000, v116
	v_lshlrev_b32_e32 v121, 16, v117
	v_and_b32_e32 v117, 0xffff0000, v117
	s_waitcnt vmcnt(0)
	v_lshlrev_b32_e32 v122, 16, v118
	v_and_b32_e32 v118, 0xffff0000, v118
	v_lshlrev_b32_e32 v123, 16, v119
	v_and_b32_e32 v119, 0xffff0000, v119
	v_mul_f32_e32 v94, v94, v120
	v_mul_f32_e32 v95, v95, v116
	v_mul_f32_e32 v96, v96, v121
	v_mul_f32_e32 v97, v97, v117
	v_mul_f32_e32 v116, v90, v122
	v_mul_f32_e32 v117, v91, v118
	v_mul_f32_e32 v118, v92, v123
	v_mul_f32_e32 v119, v93, v119
	v_pk_add_f32 v[92:93], v[106:107], v[96:97]
	v_pk_add_f32 v[90:91], v[104:105], v[94:95]
	v_pk_add_f32 v[96:97], v[102:103], v[118:119]
	v_pk_add_f32 v[94:95], v[100:101], v[116:117]
	v_cvt_pk_bf16_f32 v100, v90, v91
	v_cvt_pk_bf16_f32 v101, v92, v93
	v_cvt_pk_bf16_f32 v102, v94, v95
	v_cvt_pk_bf16_f32 v103, v96, v97
	global_store_dwordx4 v[110:111], v[90:93], off
	global_store_dwordx4 v[110:111], v[94:97], off offset:16
	global_store_dwordx4 v[108:109], v[100:103], off
	global_load_dwordx4 v[100:103], v[112:113], off offset:528
	s_nop 0
	global_load_dwordx4 v[104:107], v[112:113], off offset:512
	s_nop 0
	global_load_dwordx4 v[112:115], v[114:115], off offset:256 sc1
	v_mul_f32_e32 v91, v91, v91
	v_mul_f32_e32 v93, v93, v93
	v_mul_f32_e32 v95, v95, v95
	v_mul_f32_e32 v97, v97, v97
	v_fmac_f32_e32 v91, v90, v90
	v_fmac_f32_e32 v93, v92, v92
	v_fmac_f32_e32 v95, v94, v94
	v_fmac_f32_e32 v97, v96, v96
	v_add_f32_e32 v90, v91, v93
	v_add_f32_e32 v91, v95, v97
	v_add_f32_e32 v94, v90, v91
	s_waitcnt vmcnt(0)
	v_lshlrev_b32_e32 v90, 16, v112
	v_and_b32_e32 v91, 0xffff0000, v112
	v_lshlrev_b32_e32 v92, 16, v113
	v_and_b32_e32 v93, 0xffff0000, v113
	s_waitcnt vmcnt(0)
	v_lshlrev_b32_e32 v95, 16, v114
	v_and_b32_e32 v96, 0xffff0000, v114
	v_lshlrev_b32_e32 v97, 16, v115
	v_and_b32_e32 v112, 0xffff0000, v115
	v_mul_f32_e32 v86, v86, v90
	v_mul_f32_e32 v87, v87, v91
	v_mul_f32_e32 v88, v88, v92
	v_mul_f32_e32 v89, v89, v93
	v_mul_f32_e32 v90, v82, v95
	v_mul_f32_e32 v91, v83, v96
	v_mul_f32_e32 v92, v84, v97
	v_mul_f32_e32 v93, v85, v112
	v_pk_add_f32 v[84:85], v[106:107], v[88:89]
	v_pk_add_f32 v[82:83], v[104:105], v[86:87]
	v_pk_add_f32 v[88:89], v[102:103], v[92:93]
	v_pk_add_f32 v[86:87], v[100:101], v[90:91]
	global_store_dwordx4 v[110:111], v[82:85], off offset:512
	global_store_dwordx4 v[110:111], v[86:89], off offset:528
	v_cvt_pk_bf16_f32 v90, v82, v83
	v_cvt_pk_bf16_f32 v91, v84, v85
	v_cvt_pk_bf16_f32 v92, v86, v87
	v_cvt_pk_bf16_f32 v93, v88, v89
	v_mul_f32_e32 v83, v83, v83
	v_mul_f32_e32 v85, v85, v85
	v_mul_f32_e32 v87, v87, v87
	v_mul_f32_e32 v89, v89, v89
	v_fmac_f32_e32 v83, v82, v82
	v_fmac_f32_e32 v85, v84, v84
	v_fmac_f32_e32 v87, v86, v86
	v_fmac_f32_e32 v89, v88, v88
	global_store_dwordx4 v[108:109], v[90:93], off offset:256
	v_mbcnt_lo_u32_b32 v82, -1, 0
	v_mbcnt_hi_u32_b32 v82, -1, v82
	v_add_f32_e32 v83, v83, v85
	v_add_f32_e32 v84, v87, v89
	v_lshlrev_b32_e32 v82, 2, v82
	v_add_f32_e32 v83, v83, v84
	v_xor_b32_e32 v82, 64, v82
	v_add_f32_e32 v83, v94, v83
	ds_bpermute_b32 v82, v82, v83
	s_waitcnt lgkmcnt(0)
	v_add_f32_e32 v82, v83, v82
	v_mov_b32_e32 v83, v82
	s_nop 1
	v_permlane32_swap_b32_e32 v82, v83
	s_and_saveexec_b64 s[26:27], s[42:43]
	s_cbranch_execz .LBB0_931
	v_lshlrev_b64 v[84:85], 6, v[98:99]
	v_lshl_add_u64 v[84:85], s[38:39], 0, v[84:85]
	v_lshl_add_u64 v[84:85], s[60:61], 2, v[84:85]
	s_lshl_b32 s90, s73, 2
	v_lshl_add_u64 v[84:85], v[84:85], 0, s[90:91]
	v_add_f32_e32 v82, v82, v83
	global_store_dword v[84:85], v82, off
.LBB0_931:
	s_or_b64 exec, exec, s[26:27]
	v_or_b32_e32 v82, 48, v138
	v_ashrrev_i32_e32 v83, 31, v82
	v_lshlrev_b64 v[84:85], 10, v[82:83]
	v_lshl_add_u64 v[92:93], v[84:85], 0, v[136:137]
	v_lshlrev_b64 v[94:95], 2, v[92:93]
	v_lshlrev_b64 v[92:93], 1, v[92:93]
	v_lshl_add_u64 v[96:97], s[28:29], 0, v[94:95]
	v_lshl_add_u64 v[98:99], s[46:47], 0, v[92:93]
	global_load_dwordx4 v[84:87], v[96:97], off offset:16
	global_load_dwordx4 v[88:91], v[96:97], off
	global_load_dwordx4 v[100:103], v[98:99], off sc1
	v_lshl_add_u64 v[94:95], s[34:35], 0, v[94:95]
	v_lshl_add_u64 v[92:93], s[36:37], 0, v[92:93]
	s_waitcnt vmcnt(0)
	v_lshlrev_b32_e32 v104, 16, v100
	v_and_b32_e32 v100, 0xffff0000, v100
	v_lshlrev_b32_e32 v105, 16, v101
	v_and_b32_e32 v101, 0xffff0000, v101
	s_waitcnt vmcnt(0)
	v_lshlrev_b32_e32 v106, 16, v102
	v_and_b32_e32 v102, 0xffff0000, v102
	v_lshlrev_b32_e32 v107, 16, v103
	v_and_b32_e32 v103, 0xffff0000, v103
	v_mul_f32_e32 v78, v78, v104
	v_mul_f32_e32 v79, v79, v100
	v_mul_f32_e32 v80, v80, v105
	v_mul_f32_e32 v81, v81, v101
	v_mul_f32_e32 v100, v74, v106
	v_mul_f32_e32 v101, v75, v102
	v_mul_f32_e32 v102, v76, v107
	v_mul_f32_e32 v103, v77, v103
	v_pk_add_f32 v[76:77], v[90:91], v[80:81]
	v_pk_add_f32 v[74:75], v[88:89], v[78:79]
	v_pk_add_f32 v[80:81], v[86:87], v[102:103]
	v_pk_add_f32 v[78:79], v[84:85], v[100:101]
	v_cvt_pk_bf16_f32 v84, v74, v75
	v_cvt_pk_bf16_f32 v85, v76, v77
	v_cvt_pk_bf16_f32 v86, v78, v79
	v_cvt_pk_bf16_f32 v87, v80, v81
	global_store_dwordx4 v[94:95], v[74:77], off
	global_store_dwordx4 v[94:95], v[78:81], off offset:16
	global_store_dwordx4 v[92:93], v[84:87], off
	global_load_dwordx4 v[84:87], v[96:97], off offset:528
	s_nop 0
	global_load_dwordx4 v[88:91], v[96:97], off offset:512
	s_nop 0
	global_load_dwordx4 v[96:99], v[98:99], off offset:256 sc1
	v_mul_f32_e32 v75, v75, v75
	v_mul_f32_e32 v77, v77, v77
	v_mul_f32_e32 v79, v79, v79
	v_mul_f32_e32 v81, v81, v81
	v_fmac_f32_e32 v75, v74, v74
	v_fmac_f32_e32 v77, v76, v76
	v_fmac_f32_e32 v79, v78, v78
	v_fmac_f32_e32 v81, v80, v80
	v_add_f32_e32 v74, v75, v77
	v_add_f32_e32 v75, v79, v81
	v_add_f32_e32 v78, v74, v75
	s_waitcnt vmcnt(0)
	v_lshlrev_b32_e32 v74, 16, v96
	v_and_b32_e32 v75, 0xffff0000, v96
	v_lshlrev_b32_e32 v76, 16, v97
	v_and_b32_e32 v77, 0xffff0000, v97
	s_waitcnt vmcnt(0)
	v_lshlrev_b32_e32 v79, 16, v98
	v_and_b32_e32 v80, 0xffff0000, v98
	v_lshlrev_b32_e32 v81, 16, v99
	v_and_b32_e32 v96, 0xffff0000, v99
	v_mul_f32_e32 v70, v70, v74
	v_mul_f32_e32 v71, v71, v75
	v_mul_f32_e32 v72, v72, v76
	v_mul_f32_e32 v73, v73, v77
	v_mul_f32_e32 v74, v66, v79
	v_mul_f32_e32 v75, v67, v80
	v_mul_f32_e32 v76, v68, v81
	v_mul_f32_e32 v77, v69, v96
	v_pk_add_f32 v[68:69], v[90:91], v[72:73]
	v_pk_add_f32 v[66:67], v[88:89], v[70:71]
	v_pk_add_f32 v[72:73], v[86:87], v[76:77]
	v_pk_add_f32 v[70:71], v[84:85], v[74:75]
	global_store_dwordx4 v[94:95], v[66:69], off offset:512
	global_store_dwordx4 v[94:95], v[70:73], off offset:528
	v_cvt_pk_bf16_f32 v74, v66, v67
	v_cvt_pk_bf16_f32 v75, v68, v69
	v_cvt_pk_bf16_f32 v76, v70, v71
	v_cvt_pk_bf16_f32 v77, v72, v73
	v_mul_f32_e32 v67, v67, v67
	v_mul_f32_e32 v69, v69, v69
	v_mul_f32_e32 v71, v71, v71
	v_mul_f32_e32 v73, v73, v73
	v_fmac_f32_e32 v67, v66, v66
	v_fmac_f32_e32 v69, v68, v68
	v_fmac_f32_e32 v71, v70, v70
	v_fmac_f32_e32 v73, v72, v72
	global_store_dwordx4 v[92:93], v[74:77], off offset:256
	v_mbcnt_lo_u32_b32 v66, -1, 0
	v_mbcnt_hi_u32_b32 v66, -1, v66
	v_add_f32_e32 v67, v67, v69
	v_add_f32_e32 v68, v71, v73
	v_lshlrev_b32_e32 v66, 2, v66
	v_add_f32_e32 v67, v67, v68
	v_xor_b32_e32 v66, 64, v66
	v_add_f32_e32 v67, v78, v67
	ds_bpermute_b32 v66, v66, v67
	s_waitcnt lgkmcnt(0)
	v_add_f32_e32 v66, v67, v66
	v_mov_b32_e32 v67, v66
	s_nop 1
	v_permlane32_swap_b32_e32 v66, v67
	s_and_saveexec_b64 s[26:27], s[42:43]
	s_cbranch_execz .LBB0_933
	v_lshlrev_b64 v[68:69], 6, v[82:83]
	v_lshl_add_u64 v[68:69], s[38:39], 0, v[68:69]
	v_lshl_add_u64 v[68:69], s[60:61], 2, v[68:69]
	s_lshl_b32 s90, s73, 2
	v_lshl_add_u64 v[68:69], v[68:69], 0, s[90:91]
	v_add_f32_e32 v66, v66, v67
	global_store_dword v[68:69], v66, off
.LBB0_933:
	s_or_b64 exec, exec, s[26:27]
	v_add_u32_e32 v66, 0x80, v138
	v_ashrrev_i32_e32 v67, 31, v66
	v_lshlrev_b64 v[68:69], 10, v[66:67]
	v_lshl_add_u64 v[68:69], v[68:69], 0, v[136:137]
	v_lshlrev_b64 v[70:71], 2, v[68:69]
	v_lshlrev_b64 v[84:85], 1, v[68:69]
	v_lshl_add_u64 v[72:73], s[28:29], 0, v[70:71]
	v_lshl_add_u64 v[74:75], s[46:47], 0, v[84:85]
	global_load_dwordx4 v[76:79], v[72:73], off offset:16
	global_load_dwordx4 v[80:83], v[72:73], off
	global_load_dwordx4 v[86:89], v[74:75], off sc1
	v_lshl_add_u64 v[68:69], s[34:35], 0, v[70:71]
	v_lshl_add_u64 v[70:71], s[36:37], 0, v[84:85]
	s_waitcnt vmcnt(0)
	v_lshlrev_b32_e32 v84, 16, v86
	v_and_b32_e32 v85, 0xffff0000, v86
	v_lshlrev_b32_e32 v86, 16, v87
	v_and_b32_e32 v87, 0xffff0000, v87
	s_waitcnt vmcnt(0)
	v_lshlrev_b32_e32 v90, 16, v88
	v_and_b32_e32 v88, 0xffff0000, v88
	v_lshlrev_b32_e32 v91, 16, v89
	v_and_b32_e32 v89, 0xffff0000, v89
	v_mul_f32_e32 v62, v62, v84
	v_mul_f32_e32 v63, v63, v85
	v_mul_f32_e32 v64, v64, v86
	v_mul_f32_e32 v65, v65, v87
	v_mul_f32_e32 v84, v58, v90
	v_mul_f32_e32 v85, v59, v88
	v_mul_f32_e32 v86, v60, v91
	v_mul_f32_e32 v87, v61, v89
	v_pk_add_f32 v[60:61], v[82:83], v[64:65]
	v_pk_add_f32 v[58:59], v[80:81], v[62:63]
	v_pk_add_f32 v[64:65], v[78:79], v[86:87]
	v_pk_add_f32 v[62:63], v[76:77], v[84:85]
	v_cvt_pk_bf16_f32 v76, v58, v59
	v_cvt_pk_bf16_f32 v77, v60, v61
	v_cvt_pk_bf16_f32 v78, v62, v63
	v_cvt_pk_bf16_f32 v79, v64, v65
	global_store_dwordx4 v[68:69], v[58:61], off
	global_store_dwordx4 v[68:69], v[62:65], off offset:16
	global_store_dwordx4 v[70:71], v[76:79], off
	global_load_dwordx4 v[76:79], v[72:73], off offset:528
	s_nop 0
	global_load_dwordx4 v[80:83], v[72:73], off offset:512
	s_nop 0
	global_load_dwordx4 v[72:75], v[74:75], off offset:256 sc1
	v_mul_f32_e32 v59, v59, v59
	v_mul_f32_e32 v61, v61, v61
	v_mul_f32_e32 v63, v63, v63
	v_mul_f32_e32 v65, v65, v65
	v_fmac_f32_e32 v59, v58, v58
	v_fmac_f32_e32 v61, v60, v60
	v_fmac_f32_e32 v63, v62, v62
	v_fmac_f32_e32 v65, v64, v64
	v_add_f32_e32 v58, v59, v61
	v_add_f32_e32 v59, v63, v65
	v_add_f32_e32 v62, v58, v59
	s_waitcnt vmcnt(0)
	v_lshlrev_b32_e32 v58, 16, v72
	v_and_b32_e32 v59, 0xffff0000, v72
	v_lshlrev_b32_e32 v60, 16, v73
	v_and_b32_e32 v61, 0xffff0000, v73
	s_waitcnt vmcnt(0)
	v_lshlrev_b32_e32 v63, 16, v74
	v_and_b32_e32 v64, 0xffff0000, v74
	v_lshlrev_b32_e32 v65, 16, v75
	v_and_b32_e32 v72, 0xffff0000, v75
	v_mul_f32_e32 v54, v54, v58
	v_mul_f32_e32 v55, v55, v59
	v_mul_f32_e32 v56, v56, v60
	v_mul_f32_e32 v57, v57, v61
	v_mul_f32_e32 v58, v50, v63
	v_mul_f32_e32 v59, v51, v64
	v_mul_f32_e32 v60, v52, v65
	v_mul_f32_e32 v61, v53, v72
	v_pk_add_f32 v[52:53], v[82:83], v[56:57]
	v_pk_add_f32 v[50:51], v[80:81], v[54:55]
	v_pk_add_f32 v[56:57], v[78:79], v[60:61]
	v_pk_add_f32 v[54:55], v[76:77], v[58:59]
	global_store_dwordx4 v[68:69], v[50:53], off offset:512
	global_store_dwordx4 v[68:69], v[54:57], off offset:528
	v_cvt_pk_bf16_f32 v58, v50, v51
	v_cvt_pk_bf16_f32 v59, v52, v53
	v_cvt_pk_bf16_f32 v60, v54, v55
	v_cvt_pk_bf16_f32 v61, v56, v57
	v_mul_f32_e32 v51, v51, v51
	v_mul_f32_e32 v53, v53, v53
	v_mul_f32_e32 v55, v55, v55
	v_mul_f32_e32 v57, v57, v57
	v_fmac_f32_e32 v51, v50, v50
	v_fmac_f32_e32 v53, v52, v52
	v_fmac_f32_e32 v55, v54, v54
	v_fmac_f32_e32 v57, v56, v56
	global_store_dwordx4 v[70:71], v[58:61], off offset:256
	v_mbcnt_lo_u32_b32 v50, -1, 0
	v_mbcnt_hi_u32_b32 v50, -1, v50
	v_add_f32_e32 v51, v51, v53
	v_add_f32_e32 v52, v55, v57
	v_lshlrev_b32_e32 v50, 2, v50
	v_add_f32_e32 v51, v51, v52
	v_xor_b32_e32 v50, 64, v50
	v_add_f32_e32 v51, v62, v51
	ds_bpermute_b32 v50, v50, v51
	s_waitcnt lgkmcnt(0)
	v_add_f32_e32 v50, v51, v50
	v_mov_b32_e32 v51, v50
	s_nop 1
	v_permlane32_swap_b32_e32 v50, v51
	s_and_saveexec_b64 s[26:27], s[42:43]
	s_cbranch_execz .LBB0_935
	v_lshlrev_b64 v[52:53], 6, v[66:67]
	v_lshl_add_u64 v[52:53], s[38:39], 0, v[52:53]
	v_lshl_add_u64 v[52:53], s[60:61], 2, v[52:53]
	s_lshl_b32 s90, s73, 2
	v_lshl_add_u64 v[52:53], v[52:53], 0, s[90:91]
	v_add_f32_e32 v50, v50, v51
	global_store_dword v[52:53], v50, off
.LBB0_935:
	s_or_b64 exec, exec, s[26:27]
	v_add_u32_e32 v50, 0x90, v138
	v_ashrrev_i32_e32 v51, 31, v50
	v_lshlrev_b64 v[52:53], 10, v[50:51]
	v_lshl_add_u64 v[60:61], v[52:53], 0, v[136:137]
	v_lshlrev_b64 v[62:63], 2, v[60:61]
	v_lshlrev_b64 v[60:61], 1, v[60:61]
	v_lshl_add_u64 v[64:65], s[28:29], 0, v[62:63]
	v_lshl_add_u64 v[66:67], s[46:47], 0, v[60:61]
	global_load_dwordx4 v[52:55], v[64:65], off offset:16
	global_load_dwordx4 v[56:59], v[64:65], off
	global_load_dwordx4 v[68:71], v[66:67], off sc1
	v_lshl_add_u64 v[62:63], s[34:35], 0, v[62:63]
	v_lshl_add_u64 v[60:61], s[36:37], 0, v[60:61]
	s_waitcnt vmcnt(0)
	v_lshlrev_b32_e32 v72, 16, v68
	v_and_b32_e32 v68, 0xffff0000, v68
	v_lshlrev_b32_e32 v73, 16, v69
	v_and_b32_e32 v69, 0xffff0000, v69
	s_waitcnt vmcnt(0)
	v_lshlrev_b32_e32 v74, 16, v70
	v_and_b32_e32 v70, 0xffff0000, v70
	v_lshlrev_b32_e32 v75, 16, v71
	v_and_b32_e32 v71, 0xffff0000, v71
	v_mul_f32_e32 v46, v46, v72
	v_mul_f32_e32 v47, v47, v68
	v_mul_f32_e32 v48, v48, v73
	v_mul_f32_e32 v49, v49, v69
	v_mul_f32_e32 v68, v42, v74
	v_mul_f32_e32 v69, v43, v70
	v_mul_f32_e32 v70, v44, v75
	v_mul_f32_e32 v71, v45, v71
	v_pk_add_f32 v[44:45], v[58:59], v[48:49]
	v_pk_add_f32 v[42:43], v[56:57], v[46:47]
	v_pk_add_f32 v[48:49], v[54:55], v[70:71]
	v_pk_add_f32 v[46:47], v[52:53], v[68:69]
	v_cvt_pk_bf16_f32 v52, v42, v43
	v_cvt_pk_bf16_f32 v53, v44, v45
	v_cvt_pk_bf16_f32 v54, v46, v47
	v_cvt_pk_bf16_f32 v55, v48, v49
	global_store_dwordx4 v[62:63], v[42:45], off
	global_store_dwordx4 v[62:63], v[46:49], off offset:16
	global_store_dwordx4 v[60:61], v[52:55], off
	global_load_dwordx4 v[52:55], v[64:65], off offset:528
	s_nop 0
	global_load_dwordx4 v[56:59], v[64:65], off offset:512
	s_nop 0
	global_load_dwordx4 v[64:67], v[66:67], off offset:256 sc1
	v_mul_f32_e32 v43, v43, v43
	v_mul_f32_e32 v45, v45, v45
	v_mul_f32_e32 v47, v47, v47
	v_mul_f32_e32 v49, v49, v49
	v_fmac_f32_e32 v43, v42, v42
	v_fmac_f32_e32 v45, v44, v44
	v_fmac_f32_e32 v47, v46, v46
	v_fmac_f32_e32 v49, v48, v48
	v_add_f32_e32 v42, v43, v45
	v_add_f32_e32 v43, v47, v49
	v_add_f32_e32 v46, v42, v43
	s_waitcnt vmcnt(0)
	v_lshlrev_b32_e32 v42, 16, v64
	v_and_b32_e32 v43, 0xffff0000, v64
	v_lshlrev_b32_e32 v44, 16, v65
	v_and_b32_e32 v45, 0xffff0000, v65
	s_waitcnt vmcnt(0)
	v_lshlrev_b32_e32 v47, 16, v66
	v_and_b32_e32 v48, 0xffff0000, v66
	v_lshlrev_b32_e32 v49, 16, v67
	v_and_b32_e32 v64, 0xffff0000, v67
	v_mul_f32_e32 v38, v38, v42
	v_mul_f32_e32 v39, v39, v43
	v_mul_f32_e32 v40, v40, v44
	v_mul_f32_e32 v41, v41, v45
	v_mul_f32_e32 v42, v34, v47
	v_mul_f32_e32 v43, v35, v48
	v_mul_f32_e32 v44, v36, v49
	v_mul_f32_e32 v45, v37, v64
	v_pk_add_f32 v[36:37], v[58:59], v[40:41]
	v_pk_add_f32 v[34:35], v[56:57], v[38:39]
	v_pk_add_f32 v[40:41], v[54:55], v[44:45]
	v_pk_add_f32 v[38:39], v[52:53], v[42:43]
	global_store_dwordx4 v[62:63], v[34:37], off offset:512
	global_store_dwordx4 v[62:63], v[38:41], off offset:528
	v_cvt_pk_bf16_f32 v42, v34, v35
	v_cvt_pk_bf16_f32 v43, v36, v37
	v_cvt_pk_bf16_f32 v44, v38, v39
	v_cvt_pk_bf16_f32 v45, v40, v41
	v_mul_f32_e32 v35, v35, v35
	v_mul_f32_e32 v37, v37, v37
	v_mul_f32_e32 v39, v39, v39
	v_mul_f32_e32 v41, v41, v41
	v_fmac_f32_e32 v35, v34, v34
	v_fmac_f32_e32 v37, v36, v36
	v_fmac_f32_e32 v39, v38, v38
	v_fmac_f32_e32 v41, v40, v40
	global_store_dwordx4 v[60:61], v[42:45], off offset:256
	v_mbcnt_lo_u32_b32 v34, -1, 0
	v_mbcnt_hi_u32_b32 v34, -1, v34
	v_add_f32_e32 v35, v35, v37
	v_add_f32_e32 v36, v39, v41
	v_lshlrev_b32_e32 v34, 2, v34
	v_add_f32_e32 v35, v35, v36
	v_xor_b32_e32 v34, 64, v34
	v_add_f32_e32 v35, v46, v35
	ds_bpermute_b32 v34, v34, v35
	s_waitcnt lgkmcnt(0)
	v_add_f32_e32 v34, v35, v34
	v_mov_b32_e32 v35, v34
	s_nop 1
	v_permlane32_swap_b32_e32 v34, v35
	s_and_saveexec_b64 s[26:27], s[42:43]
	s_cbranch_execz .LBB0_937
	v_lshlrev_b64 v[36:37], 6, v[50:51]
	v_lshl_add_u64 v[36:37], s[38:39], 0, v[36:37]
	v_lshl_add_u64 v[36:37], s[60:61], 2, v[36:37]
	s_lshl_b32 s90, s73, 2
	v_lshl_add_u64 v[36:37], v[36:37], 0, s[90:91]
	v_add_f32_e32 v34, v34, v35
	global_store_dword v[36:37], v34, off
.LBB0_937:
	s_or_b64 exec, exec, s[26:27]
	v_add_u32_e32 v34, 0xa0, v138
	v_ashrrev_i32_e32 v35, 31, v34
	v_lshlrev_b64 v[36:37], 10, v[34:35]
	v_lshl_add_u64 v[36:37], v[36:37], 0, v[136:137]
	v_lshlrev_b64 v[38:39], 2, v[36:37]
	v_lshlrev_b64 v[52:53], 1, v[36:37]
	v_lshl_add_u64 v[40:41], s[28:29], 0, v[38:39]
	v_lshl_add_u64 v[42:43], s[46:47], 0, v[52:53]
	global_load_dwordx4 v[44:47], v[40:41], off offset:16
	global_load_dwordx4 v[48:51], v[40:41], off
	global_load_dwordx4 v[54:57], v[42:43], off sc1
	v_lshl_add_u64 v[36:37], s[34:35], 0, v[38:39]
	v_lshl_add_u64 v[38:39], s[36:37], 0, v[52:53]
	s_waitcnt vmcnt(0)
	v_lshlrev_b32_e32 v52, 16, v54
	v_and_b32_e32 v53, 0xffff0000, v54
	v_lshlrev_b32_e32 v54, 16, v55
	v_and_b32_e32 v55, 0xffff0000, v55
	s_waitcnt vmcnt(0)
	v_lshlrev_b32_e32 v58, 16, v56
	v_and_b32_e32 v56, 0xffff0000, v56
	v_lshlrev_b32_e32 v59, 16, v57
	v_and_b32_e32 v57, 0xffff0000, v57
	v_mul_f32_e32 v30, v30, v52
	v_mul_f32_e32 v31, v31, v53
	v_mul_f32_e32 v32, v32, v54
	v_mul_f32_e32 v33, v33, v55
	v_mul_f32_e32 v52, v26, v58
	v_mul_f32_e32 v53, v27, v56
	v_mul_f32_e32 v54, v28, v59
	v_mul_f32_e32 v55, v29, v57
	v_pk_add_f32 v[28:29], v[50:51], v[32:33]
	v_pk_add_f32 v[26:27], v[48:49], v[30:31]
	v_pk_add_f32 v[32:33], v[46:47], v[54:55]
	v_pk_add_f32 v[30:31], v[44:45], v[52:53]
	v_cvt_pk_bf16_f32 v44, v26, v27
	v_cvt_pk_bf16_f32 v45, v28, v29
	v_cvt_pk_bf16_f32 v46, v30, v31
	v_cvt_pk_bf16_f32 v47, v32, v33
	global_store_dwordx4 v[36:37], v[26:29], off
	global_store_dwordx4 v[36:37], v[30:33], off offset:16
	global_store_dwordx4 v[38:39], v[44:47], off
	global_load_dwordx4 v[44:47], v[40:41], off offset:528
	s_nop 0
	global_load_dwordx4 v[48:51], v[40:41], off offset:512
	s_nop 0
	global_load_dwordx4 v[40:43], v[42:43], off offset:256 sc1
	v_mul_f32_e32 v27, v27, v27
	v_mul_f32_e32 v29, v29, v29
	v_mul_f32_e32 v31, v31, v31
	v_mul_f32_e32 v33, v33, v33
	v_fmac_f32_e32 v27, v26, v26
	v_fmac_f32_e32 v29, v28, v28
	v_fmac_f32_e32 v31, v30, v30
	v_fmac_f32_e32 v33, v32, v32
	v_add_f32_e32 v26, v27, v29
	v_add_f32_e32 v27, v31, v33
	v_add_f32_e32 v30, v26, v27
	s_waitcnt vmcnt(0)
	v_lshlrev_b32_e32 v26, 16, v40
	v_and_b32_e32 v27, 0xffff0000, v40
	v_lshlrev_b32_e32 v28, 16, v41
	v_and_b32_e32 v29, 0xffff0000, v41
	s_waitcnt vmcnt(0)
	v_lshlrev_b32_e32 v31, 16, v42
	v_and_b32_e32 v32, 0xffff0000, v42
	v_lshlrev_b32_e32 v33, 16, v43
	v_and_b32_e32 v40, 0xffff0000, v43
	v_mul_f32_e32 v22, v22, v26
	v_mul_f32_e32 v23, v23, v27
	v_mul_f32_e32 v24, v24, v28
	v_mul_f32_e32 v25, v25, v29
	v_mul_f32_e32 v26, v18, v31
	v_mul_f32_e32 v27, v19, v32
	v_mul_f32_e32 v28, v20, v33
	v_mul_f32_e32 v29, v21, v40
	v_pk_add_f32 v[20:21], v[50:51], v[24:25]
	v_pk_add_f32 v[18:19], v[48:49], v[22:23]
	v_pk_add_f32 v[24:25], v[46:47], v[28:29]
	v_pk_add_f32 v[22:23], v[44:45], v[26:27]
	global_store_dwordx4 v[36:37], v[18:21], off offset:512
	global_store_dwordx4 v[36:37], v[22:25], off offset:528
	v_cvt_pk_bf16_f32 v26, v18, v19
	v_cvt_pk_bf16_f32 v27, v20, v21
	v_cvt_pk_bf16_f32 v28, v22, v23
	v_cvt_pk_bf16_f32 v29, v24, v25
	v_mul_f32_e32 v19, v19, v19
	v_mul_f32_e32 v21, v21, v21
	v_mul_f32_e32 v23, v23, v23
	v_mul_f32_e32 v25, v25, v25
	v_fmac_f32_e32 v19, v18, v18
	v_fmac_f32_e32 v21, v20, v20
	v_fmac_f32_e32 v23, v22, v22
	v_fmac_f32_e32 v25, v24, v24
	global_store_dwordx4 v[38:39], v[26:29], off offset:256
	v_mbcnt_lo_u32_b32 v18, -1, 0
	v_mbcnt_hi_u32_b32 v18, -1, v18
	v_add_f32_e32 v19, v19, v21
	v_add_f32_e32 v20, v23, v25
	v_lshlrev_b32_e32 v18, 2, v18
	v_add_f32_e32 v19, v19, v20
	v_xor_b32_e32 v18, 64, v18
	v_add_f32_e32 v19, v30, v19
	ds_bpermute_b32 v18, v18, v19
	s_waitcnt lgkmcnt(0)
	v_add_f32_e32 v18, v19, v18
	v_mov_b32_e32 v19, v18
	s_nop 1
	v_permlane32_swap_b32_e32 v18, v19
	s_and_saveexec_b64 s[26:27], s[42:43]
	s_cbranch_execz .LBB0_939
	v_lshlrev_b64 v[20:21], 6, v[34:35]
	v_lshl_add_u64 v[20:21], s[38:39], 0, v[20:21]
	v_lshl_add_u64 v[20:21], s[60:61], 2, v[20:21]
	s_lshl_b32 s90, s73, 2
	v_lshl_add_u64 v[20:21], v[20:21], 0, s[90:91]
	v_add_f32_e32 v18, v18, v19
	global_store_dword v[20:21], v18, off
.LBB0_939:
	s_or_b64 exec, exec, s[26:27]
	v_add_u32_e32 v18, 0xb0, v138
	v_ashrrev_i32_e32 v19, 31, v18
	v_lshlrev_b64 v[20:21], 10, v[18:19]
	v_lshl_add_u64 v[28:29], v[20:21], 0, v[136:137]
	v_lshlrev_b64 v[30:31], 2, v[28:29]
	v_lshlrev_b64 v[28:29], 1, v[28:29]
	v_lshl_add_u64 v[32:33], s[28:29], 0, v[30:31]
	v_lshl_add_u64 v[34:35], s[46:47], 0, v[28:29]
	global_load_dwordx4 v[20:23], v[32:33], off offset:16
	global_load_dwordx4 v[24:27], v[32:33], off
	global_load_dwordx4 v[36:39], v[34:35], off sc1
	v_lshl_add_u64 v[30:31], s[34:35], 0, v[30:31]
	v_lshl_add_u64 v[28:29], s[36:37], 0, v[28:29]
	s_waitcnt vmcnt(0)
	v_lshlrev_b32_e32 v40, 16, v36
	v_and_b32_e32 v36, 0xffff0000, v36
	v_lshlrev_b32_e32 v41, 16, v37
	v_and_b32_e32 v37, 0xffff0000, v37
	s_waitcnt vmcnt(0)
	v_lshlrev_b32_e32 v42, 16, v38
	v_and_b32_e32 v38, 0xffff0000, v38
	v_lshlrev_b32_e32 v43, 16, v39
	v_and_b32_e32 v39, 0xffff0000, v39
	v_mul_f32_e32 v14, v14, v40
	v_mul_f32_e32 v15, v15, v36
	v_mul_f32_e32 v16, v16, v41
	v_mul_f32_e32 v17, v17, v37
	v_mul_f32_e32 v36, v10, v42
	v_mul_f32_e32 v37, v11, v38
	v_mul_f32_e32 v38, v12, v43
	v_mul_f32_e32 v39, v13, v39
	v_pk_add_f32 v[12:13], v[26:27], v[16:17]
	v_pk_add_f32 v[10:11], v[24:25], v[14:15]
	v_pk_add_f32 v[16:17], v[22:23], v[38:39]
	v_pk_add_f32 v[14:15], v[20:21], v[36:37]
	v_cvt_pk_bf16_f32 v20, v10, v11
	v_cvt_pk_bf16_f32 v21, v12, v13
	v_cvt_pk_bf16_f32 v22, v14, v15
	v_cvt_pk_bf16_f32 v23, v16, v17
	global_store_dwordx4 v[30:31], v[10:13], off
	global_store_dwordx4 v[30:31], v[14:17], off offset:16
	global_store_dwordx4 v[28:29], v[20:23], off
	global_load_dwordx4 v[20:23], v[32:33], off offset:528
	s_nop 0
	global_load_dwordx4 v[24:27], v[32:33], off offset:512
	s_nop 0
	global_load_dwordx4 v[32:35], v[34:35], off offset:256 sc1
	v_mul_f32_e32 v11, v11, v11
	v_mul_f32_e32 v13, v13, v13
	v_mul_f32_e32 v15, v15, v15
	v_mul_f32_e32 v17, v17, v17
	v_fmac_f32_e32 v11, v10, v10
	v_fmac_f32_e32 v13, v12, v12
	v_fmac_f32_e32 v15, v14, v14
	v_fmac_f32_e32 v17, v16, v16
	v_add_f32_e32 v10, v11, v13
	v_add_f32_e32 v11, v15, v17
	v_add_f32_e32 v14, v10, v11
	s_waitcnt vmcnt(0)
	v_lshlrev_b32_e32 v10, 16, v32
	v_and_b32_e32 v11, 0xffff0000, v32
	v_lshlrev_b32_e32 v12, 16, v33
	v_and_b32_e32 v13, 0xffff0000, v33
	s_waitcnt vmcnt(0)
	v_lshlrev_b32_e32 v15, 16, v34
	v_and_b32_e32 v16, 0xffff0000, v34
	v_lshlrev_b32_e32 v17, 16, v35
	v_and_b32_e32 v32, 0xffff0000, v35
	v_mul_f32_e32 v6, v6, v10
	v_mul_f32_e32 v7, v7, v11
	v_mul_f32_e32 v8, v8, v12
	v_mul_f32_e32 v9, v9, v13
	v_mul_f32_e32 v10, v2, v15
	v_mul_f32_e32 v11, v3, v16
	v_mul_f32_e32 v12, v4, v17
	v_mul_f32_e32 v13, v5, v32
	v_pk_add_f32 v[4:5], v[26:27], v[8:9]
	v_pk_add_f32 v[2:3], v[24:25], v[6:7]
	v_pk_add_f32 v[8:9], v[22:23], v[12:13]
	v_pk_add_f32 v[6:7], v[20:21], v[10:11]
	global_store_dwordx4 v[30:31], v[2:5], off offset:512
	global_store_dwordx4 v[30:31], v[6:9], off offset:528
	v_cvt_pk_bf16_f32 v10, v2, v3
	v_cvt_pk_bf16_f32 v11, v4, v5
	v_cvt_pk_bf16_f32 v12, v6, v7
	v_cvt_pk_bf16_f32 v13, v8, v9
	v_mul_f32_e32 v3, v3, v3
	v_mul_f32_e32 v5, v5, v5
	v_mul_f32_e32 v7, v7, v7
	v_mul_f32_e32 v9, v9, v9
	v_fmac_f32_e32 v3, v2, v2
	v_fmac_f32_e32 v5, v4, v4
	v_fmac_f32_e32 v7, v6, v6
	v_fmac_f32_e32 v9, v8, v8
	global_store_dwordx4 v[28:29], v[10:13], off offset:256
	v_mbcnt_lo_u32_b32 v2, -1, 0
	v_mbcnt_hi_u32_b32 v2, -1, v2
	v_add_f32_e32 v3, v3, v5
	v_add_f32_e32 v4, v7, v9
	v_lshlrev_b32_e32 v2, 2, v2
	v_add_f32_e32 v3, v3, v4
	v_xor_b32_e32 v2, 64, v2
	v_add_f32_e32 v3, v14, v3
	ds_bpermute_b32 v2, v2, v3
	s_waitcnt lgkmcnt(0)
	v_add_f32_e32 v2, v3, v2
	v_mov_b32_e32 v3, v2
	s_nop 1
	v_permlane32_swap_b32_e32 v2, v3
	s_and_saveexec_b64 s[26:27], s[42:43]
	s_cbranch_execz .LBB0_941
	v_lshlrev_b64 v[4:5], 6, v[18:19]
	v_lshl_add_u64 v[4:5], s[38:39], 0, v[4:5]
	v_lshl_add_u64 v[4:5], s[60:61], 2, v[4:5]
	s_lshl_b32 s90, s73, 2
	v_lshl_add_u64 v[4:5], v[4:5], 0, s[90:91]
	v_add_f32_e32 v2, v2, v3
	global_store_dword v[4:5], v2, off
